# selected stream active-tile path: mask words once per stage, C init overlapped with K fragment reads, first group's rescale out of line, exp blocks re-spaced; on top of v34
# speedup vs baseline: 1.0107x; 1.0107x over previous
; #define LAS __attribute__((address_space(3)))
;     f4 s[2][2];
; #pragma unroll
;     for (int ch = 0; ch < 2; ++ch)
; #pragma unroll
;         for (int kt = 0; kt < 2; ++kt) { f4 t = (f4){colbias, colbias, colbias, colbias}; t = MFMA16(kf[ch][kt][0], bq[0], t); s[ch][kt] = MFMA16(kf[ch][kt][1], bq[1], t); }
;     float mx = -1e30f;
; #pragma unroll
;     for (int ch = 0; ch < 2; ++ch)
; #pragma unroll
;         for (int h = 0; h < 2; ++h) mx = fmaxf(mx, fmaxf(fmaxf(s[ch][h][0], s[ch][h][1]), fmaxf(s[ch][h][2], s[ch][h][3])));
;     if (__any(mx > a.m + MAX_SLACK)) {
;         mx = fmaxf(mx, __shfl_xor(mx, 16)); mx = fmaxf(mx, __shfl_xor(mx, 32));
;         const float mn = fmaxf(a.m, mx), alpha = fexp2(a.m - mn); a.m = mn; a.l *= alpha;
; #pragma unroll
;         for (int c = 0; c < 4; ++c) a.o[c] = a.o[c] * alpha;
;     }
;     float ps = 0.f; bf16x8 pb[2];
; #pragma unroll
;     for (int ch = 0; ch < 2; ++ch) { f4 p0, p1;
; #pragma unroll
;         for (int j = 0; j < 4; ++j) { p0[j] = fexp2(s[ch][0][j] - a.m); p1[j] = fexp2(s[ch][1][j] - a.m); ps += p0[j] + p1[j]; }
;         pb[ch] = pack8(p0, p1); }
;     a.l += ps;
; #pragma unroll
;     for (int ch = 0; ch < 2; ++ch)
; #pragma unroll
;         for (int c = 0; c < 4; ++c) a.o[c] = MFMA16(vf[ch][c], pb[ch], a.o[c]);
; __device__ __forceinline__ void nsa_block_task(Ctx& C, int task, bf16* ONSA_OUT) {
;     ...
;         stream_tiles<4>(C, src, 0, qb, bufs, [&](const LAS unsigned char* buf, int j) {
;             if ((j >> 5) != cw) { cw = j >> 5; aw0 = (unsigned)__builtin_amdgcn_readfirstlane((int)ANYM[cw]); aw1 = (unsigned)__builtin_amdgcn_readfirstlane((int)ANYM[8 + cw]); }
;             bool any[2]; any[0] = (aw0 >> (j & 31)) & 1u; any[1] = (aw1 >> (j & 31)) & 1u;
;             if (any[0] || any[1]) {
;                 bool mysel[2];
; #pragma unroll
;                 for (int cg = 0; cg < 2; ++cg) mysel[cg] = (SELM[(4 * cg + qi) * 8 + (j >> 5)] >> (j & 31)) & 1u;
;                 bf16x8 kf[2][2][2], vf[2][4]; { const int ll = launder_v(lane);
; #pragma unroll
;                     for (int ch = 0; ch < 2; ++ch) { tile_read_k(buf, ch, ll, kf[ch]); tile_read_v(buf, ch, ll, vf[ch]); } }
; #pragma unroll
;                 for (int cg = 0; cg < 2; ++cg) if (any[cg]) attn_tile64_full(a[cg], kf, vf, bq[cg], mysel[cg] ? 0.f : -3e30f);
.Ltl_have:
	ds_read2_b32 v[62:63], v171 offset1:32
	s_lshr_b32 s46, s30, s35
	s_lshr_b32 s47, s31, s35
	s_sub_i32 s3, s94, s28
	s_min_u32 s3, s3, 4
	s_lshl_b32 s3, 1, s3
	s_add_i32 s3, s3, -1
	s_and_b32 s46, s46, s3
	s_and_b32 s47, s47, s3
	s_or_b32 s48, s46, s47
	s_mov_b32 s41, s36
	s_branch .LBB0_1214
.LBB0_1211:
	v_exp_f32_e32 v140, v140
	v_exp_f32_e32 v141, v141
	v_exp_f32_e32 v142, v142
	v_exp_f32_e32 v143, v143
	v_exp_f32_e32 v144, v144
	v_exp_f32_e32 v145, v145
	v_exp_f32_e32 v146, v146
	v_exp_f32_e32 v147, v147
	v_pk_add_f32 v[2:3], v[140:141], v[142:143]
	v_cvt_pk_bf16_f32 v140, v140, v141
	v_cvt_pk_bf16_f32 v141, v142, v143
	v_cvt_pk_bf16_f32 v142, v144, v145
	v_cvt_pk_bf16_f32 v143, v146, v147
	v_pk_add_f32 v[2:3], v[2:3], v[144:145]
	v_pk_add_f32 v[2:3], v[2:3], v[146:147]
	s_waitcnt lgkmcnt(4)
	v_mfma_f32_16x16x32_bf16 v[32:35], v[116:119], v[140:143], v[32:35]
	v_exp_f32_e32 v128, v128
	v_exp_f32_e32 v129, v129
	v_mfma_f32_16x16x32_bf16 v[28:31], v[112:115], v[140:143], v[28:31]
	v_exp_f32_e32 v130, v130
	v_exp_f32_e32 v131, v131
	v_mfma_f32_16x16x32_bf16 v[24:27], v[108:111], v[140:143], v[24:27]
	v_exp_f32_e32 v120, v120
	v_exp_f32_e32 v121, v121
	v_mfma_f32_16x16x32_bf16 v[20:23], v[104:107], v[140:143], v[20:23]
	v_exp_f32_e32 v122, v122
	v_exp_f32_e32 v123, v123
	v_pk_add_f32 v[2:3], v[2:3], v[128:129]
	v_pk_add_f32 v[2:3], v[2:3], v[130:131]
	v_cvt_pk_bf16_f32 v128, v128, v129
	v_cvt_pk_bf16_f32 v129, v130, v131
	v_cvt_pk_bf16_f32 v130, v120, v121
	v_cvt_pk_bf16_f32 v131, v122, v123
	v_pk_add_f32 v[2:3], v[2:3], v[120:121]
	v_pk_add_f32 v[2:3], v[2:3], v[122:123]
	s_waitcnt lgkmcnt(0)
	v_mfma_f32_16x16x32_bf16 v[32:35], v[96:99], v[128:131], v[32:35]
	v_mfma_f32_16x16x32_bf16 v[28:31], v[100:103], v[128:131], v[28:31]
	v_mfma_f32_16x16x32_bf16 v[24:27], v[92:95], v[128:131], v[24:27]
	v_mfma_f32_16x16x32_bf16 v[20:23], v[88:91], v[128:131], v[20:23]
	v_add_f32_e32 v0, v2, v3
	v_add_f32_e32 v168, v168, v0
.LBB0_1212:
.LBB0_1213:
.LBB0_1214:
	s_cmp_eq_u32 s48, 0
	s_cbranch_scc1 .LBB0_1225
	s_ff1_i32_b32 s39, s48
	s_bitset0_b32 s48, s39
	s_lshl_b32 s3, s39, 14
	s_add_i32 s36, s41, s3
	s_add_i32 s40, s35, s39
	s_bitcmp1_b32 s46, s39
	s_cselect_b64 s[24:25], -1, 0
	s_bitcmp1_b32 s47, s39
	s_cselect_b64 s[22:23], -1, 0
	s_andn2_b64 vcc, exec, s[24:25]
	v_add_u32_e32 v89, s36, v225
	v_add_u32_e32 v0, s36, v226
	ds_read_b128 v[140:143], v89
	ds_read_b128 v[144:147], v89 offset:2048
	ds_read_b128 v[148:151], v0
	ds_read_b128 v[128:131], v0 offset:2048
	ds_read_b128 v[136:139], v89 offset:4096
	ds_read_b128 v[124:127], v89 offset:6144
	ds_read_b128 v[132:135], v0 offset:4096
	ds_read_b128 v[120:123], v0 offset:6144
	ds_read_b128 v[116:119], v89 offset:8192
	ds_read_b128 v[112:115], v89 offset:10240
	ds_read_b128 v[108:111], v89 offset:12288
	ds_read_b128 v[104:107], v89 offset:14336
	ds_read_b128 v[96:99], v0 offset:8192
	ds_read_b128 v[100:103], v0 offset:10240
	ds_read_b128 v[92:95], v0 offset:12288
	ds_read_b128 v[88:91], v0 offset:14336
	s_cbranch_vccnz .LBB0_1222
	s_waitcnt lgkmcnt(15)
	v_bfe_i32 v0, v62, s40, 1
	v_bfi_b32 v156, v0, 0, v231
	v_sub_f32_e32 v156, v156, v170
	v_mov_b32_e32 v157, v156
	v_mov_b32_e32 v158, v156
	v_mov_b32_e32 v159, v156
	s_waitcnt lgkmcnt(12)
	s_nop 0
	v_mfma_f32_16x16x32_bf16 v[152:155], v[140:143], v[4:7], v[156:159]
	v_mfma_f32_16x16x32_bf16 v[160:163], v[148:151], v[8:11], v[152:155]
	v_mfma_f32_16x16x32_bf16 v[152:155], v[144:147], v[4:7], v[156:159]
	v_mfma_f32_16x16x32_bf16 v[164:167], v[128:131], v[8:11], v[152:155]
	s_nop 5
	v_max3_f32 v0, v160, v161, v162
	v_max3_f32 v0, v0, v163, s93
	s_waitcnt lgkmcnt(8)
	v_mfma_f32_16x16x32_bf16 v[152:155], v[136:139], v[4:7], v[156:159]
	v_max3_f32 v0, v0, v164, v165
	v_max3_f32 v0, v0, v166, v167
	v_mfma_f32_16x16x32_bf16 v[156:159], v[124:127], v[4:7], v[156:159]
	v_mfma_f32_16x16x32_bf16 v[152:155], v[132:135], v[8:11], v[152:155]
	v_mfma_f32_16x16x32_bf16 v[156:159], v[120:123], v[8:11], v[156:159]
	s_nop 6
	v_max3_f32 v0, v0, v152, v153
	v_max3_f32 v0, v0, v154, v155
	v_max3_f32 v0, v0, v156, v157
	v_max3_f32 v0, v0, v158, v159
	v_cmp_lt_f32_e32 vcc, 0x41000000, v0
	s_cbranch_vccnz .Lresc0
; __device__ __forceinline__ bf16x8 pack8(const f4& a, const f4& b) { return __builtin_bit_cast(bf16x8, pack8u(a, b)); }
; __device__ __forceinline__ float fexp2(float x) { return __builtin_amdgcn_exp2f(x); }
; #define MFMA16(a, b, c) __builtin_amdgcn_mfma_f32_16x16x32_bf16((a), (b), (c), 0, 0, 0)
;     f4 s[2][2];
; #pragma unroll
;     for (int ch = 0; ch < 2; ++ch)
; #pragma unroll
;         for (int kt = 0; kt < 2; ++kt) { f4 t = (f4){colbias, colbias, colbias, colbias}; t = MFMA16(kf[ch][kt][0], bq[0], t); s[ch][kt] = MFMA16(kf[ch][kt][1], bq[1], t); }
;     float mx = -1e30f;
; #pragma unroll
;     for (int ch = 0; ch < 2; ++ch)
; #pragma unroll
;         for (int h = 0; h < 2; ++h) mx = fmaxf(mx, fmaxf(fmaxf(s[ch][h][0], s[ch][h][1]), fmaxf(s[ch][h][2], s[ch][h][3])));
;     if (__any(mx > a.m + MAX_SLACK)) {
;         mx = fmaxf(mx, __shfl_xor(mx, 16)); mx = fmaxf(mx, __shfl_xor(mx, 32));
;         const float mn = fmaxf(a.m, mx), alpha = fexp2(a.m - mn); a.m = mn; a.l *= alpha;
; #pragma unroll
;         for (int c = 0; c < 4; ++c) a.o[c] = a.o[c] * alpha;
;     }
;     float ps = 0.f; bf16x8 pb[2];
; #pragma unroll
;     for (int ch = 0; ch < 2; ++ch) { f4 p0, p1;
; #pragma unroll
;         for (int j = 0; j < 4; ++j) { p0[j] = fexp2(s[ch][0][j] - a.m); p1[j] = fexp2(s[ch][1][j] - a.m); ps += p0[j] + p1[j]; }
;         pb[ch] = pack8(p0, p1); }
;     a.l += ps;
; #pragma unroll
;     for (int ch = 0; ch < 2; ++ch)
; #pragma unroll
;         for (int c = 0; c < 4; ++c) a.o[c] = MFMA16(vf[ch][c], pb[ch], a.o[c]);
.LBB0_1221:
	v_exp_f32_e32 v160, v160
	v_exp_f32_e32 v161, v161
	v_exp_f32_e32 v162, v162
	v_exp_f32_e32 v163, v163
	v_exp_f32_e32 v164, v164
	v_exp_f32_e32 v165, v165
	v_exp_f32_e32 v166, v166
	v_exp_f32_e32 v167, v167
	v_pk_add_f32 v[172:173], v[160:161], v[162:163]
	v_cvt_pk_bf16_f32 v160, v160, v161
	v_cvt_pk_bf16_f32 v161, v162, v163
	v_cvt_pk_bf16_f32 v162, v164, v165
	v_cvt_pk_bf16_f32 v163, v166, v167
	v_pk_add_f32 v[172:173], v[172:173], v[164:165]
	v_pk_add_f32 v[172:173], v[172:173], v[166:167]
	s_waitcnt lgkmcnt(4)
	v_mfma_f32_16x16x32_bf16 v[52:55], v[116:119], v[160:163], v[52:55]
	v_exp_f32_e32 v152, v152
	v_exp_f32_e32 v153, v153
	v_mfma_f32_16x16x32_bf16 v[48:51], v[112:115], v[160:163], v[48:51]
	v_exp_f32_e32 v154, v154
	v_exp_f32_e32 v155, v155
	v_mfma_f32_16x16x32_bf16 v[44:47], v[108:111], v[160:163], v[44:47]
	v_exp_f32_e32 v156, v156
	v_exp_f32_e32 v157, v157
	v_mfma_f32_16x16x32_bf16 v[40:43], v[104:107], v[160:163], v[40:43]
	v_exp_f32_e32 v158, v158
	v_exp_f32_e32 v159, v159
	v_pk_add_f32 v[172:173], v[172:173], v[152:153]
	v_pk_add_f32 v[172:173], v[172:173], v[154:155]
	v_cvt_pk_bf16_f32 v152, v152, v153
	v_cvt_pk_bf16_f32 v153, v154, v155
	v_cvt_pk_bf16_f32 v154, v156, v157
	v_cvt_pk_bf16_f32 v155, v158, v159
	v_pk_add_f32 v[172:173], v[172:173], v[156:157]
	v_pk_add_f32 v[172:173], v[172:173], v[158:159]
	s_waitcnt lgkmcnt(0)
	v_mfma_f32_16x16x32_bf16 v[52:55], v[96:99], v[152:155], v[52:55]
	v_mfma_f32_16x16x32_bf16 v[48:51], v[100:103], v[152:155], v[48:51]
	v_mfma_f32_16x16x32_bf16 v[44:47], v[92:95], v[152:155], v[44:47]
	v_mfma_f32_16x16x32_bf16 v[40:43], v[88:91], v[152:155], v[40:43]
	v_add_f32_e32 v0, v172, v173
	v_add_f32_e32 v36, v36, v0
.LBB0_1222:
	s_andn2_b64 vcc, exec, s[22:23]
	s_cbranch_vccnz .LBB0_1212
	s_waitcnt lgkmcnt(15)
	v_bfe_i32 v0, v63, s40, 1
	v_bfi_b32 v152, v0, 0, v231
	v_sub_f32_e32 v152, v152, v169
	v_mov_b32_e32 v153, v152
	v_mov_b32_e32 v154, v152
	v_mov_b32_e32 v155, v152
	s_waitcnt lgkmcnt(12)
	s_nop 0
	v_mfma_f32_16x16x32_bf16 v[140:143], v[140:143], v[12:15], v[152:155]
	v_mfma_f32_16x16x32_bf16 v[144:147], v[144:147], v[12:15], v[152:155]
	v_mfma_f32_16x16x32_bf16 v[140:143], v[148:151], v[16:19], v[140:143]
	v_mfma_f32_16x16x32_bf16 v[144:147], v[128:131], v[16:19], v[144:147]
	s_waitcnt lgkmcnt(8)
	v_mfma_f32_16x16x32_bf16 v[128:131], v[136:139], v[12:15], v[152:155]
	s_nop 5
	v_max3_f32 v0, v140, v141, v142
	v_max3_f32 v0, v0, v143, s93
	v_mfma_f32_16x16x32_bf16 v[124:127], v[124:127], v[12:15], v[152:155]
	v_max3_f32 v0, v0, v144, v145
	v_mfma_f32_16x16x32_bf16 v[128:131], v[132:135], v[16:19], v[128:131]
	v_max3_f32 v0, v0, v146, v147
	v_mfma_f32_16x16x32_bf16 v[120:123], v[120:123], v[16:19], v[124:127]
	s_nop 5
	v_max3_f32 v0, v0, v128, v129
	v_max3_f32 v0, v0, v130, v131
	v_max3_f32 v0, v0, v120, v121
	v_max3_f32 v0, v0, v122, v123
	v_cmp_lt_f32_e32 vcc, 0x41000000, v0
	s_cbranch_vccz .LBB0_1211
	ds_bpermute_b32 v2, v217, v0
	v_max_f32_e32 v0, v0, v0
	s_waitcnt lgkmcnt(0)
	v_max_f32_e32 v2, v2, v2
	v_max_f32_e32 v0, v0, v2
	ds_bpermute_b32 v2, v219, v0
	s_waitcnt lgkmcnt(0)
	v_max3_f32 v2, 0, v0, v2
	v_sub_f32_e32 v0, 0, v2
	v_exp_f32_e32 v0, v0
	v_add_f32_e32 v169, v169, v2
	v_sub_f32_e32 v140, v140, v2
	v_sub_f32_e32 v141, v141, v2
	v_sub_f32_e32 v142, v142, v2
	v_sub_f32_e32 v143, v143, v2
	v_sub_f32_e32 v144, v144, v2
	v_sub_f32_e32 v145, v145, v2
	v_sub_f32_e32 v146, v146, v2
	v_sub_f32_e32 v147, v147, v2
	v_sub_f32_e32 v128, v128, v2
	v_sub_f32_e32 v129, v129, v2
	v_sub_f32_e32 v130, v130, v2
	v_sub_f32_e32 v131, v131, v2
	v_sub_f32_e32 v120, v120, v2
	v_sub_f32_e32 v121, v121, v2
	v_sub_f32_e32 v122, v122, v2
	v_sub_f32_e32 v123, v123, v2
	v_mul_f32_e32 v168, v168, v0
	v_pk_mul_f32 v[34:35], v[34:35], v[0:1] op_sel_hi:[1,0]
	v_pk_mul_f32 v[32:33], v[32:33], v[0:1] op_sel_hi:[1,0]
	v_pk_mul_f32 v[30:31], v[30:31], v[0:1] op_sel_hi:[1,0]
	v_pk_mul_f32 v[28:29], v[28:29], v[0:1] op_sel_hi:[1,0]
	v_pk_mul_f32 v[26:27], v[26:27], v[0:1] op_sel_hi:[1,0]
	v_pk_mul_f32 v[24:25], v[24:25], v[0:1] op_sel_hi:[1,0]
	v_pk_mul_f32 v[22:23], v[22:23], v[0:1] op_sel_hi:[1,0]
	v_pk_mul_f32 v[20:21], v[20:21], v[0:1] op_sel_hi:[1,0]
	s_branch .LBB0_1211
.Lresc0:
	ds_bpermute_b32 v2, v217, v0
	v_max_f32_e32 v0, v0, v0
	s_waitcnt lgkmcnt(0)
	v_max_f32_e32 v2, v2, v2
	v_max_f32_e32 v0, v0, v2
	ds_bpermute_b32 v2, v219, v0
	s_waitcnt lgkmcnt(0)
	v_max3_f32 v2, 0, v0, v2
	v_sub_f32_e32 v0, 0, v2
	v_exp_f32_e32 v0, v0
	v_add_f32_e32 v170, v170, v2
	v_sub_f32_e32 v160, v160, v2
	v_sub_f32_e32 v161, v161, v2
	v_sub_f32_e32 v162, v162, v2
	v_sub_f32_e32 v163, v163, v2
	v_sub_f32_e32 v164, v164, v2
	v_sub_f32_e32 v165, v165, v2
	v_sub_f32_e32 v166, v166, v2
	v_sub_f32_e32 v167, v167, v2
	v_sub_f32_e32 v152, v152, v2
	v_sub_f32_e32 v153, v153, v2
	v_sub_f32_e32 v154, v154, v2
	v_sub_f32_e32 v155, v155, v2
	v_sub_f32_e32 v156, v156, v2
	v_sub_f32_e32 v157, v157, v2
	v_sub_f32_e32 v158, v158, v2
	v_sub_f32_e32 v159, v159, v2
	v_mul_f32_e32 v36, v36, v0
	v_pk_mul_f32 v[54:55], v[54:55], v[0:1] op_sel_hi:[1,0]
	v_pk_mul_f32 v[52:53], v[52:53], v[0:1] op_sel_hi:[1,0]
	v_pk_mul_f32 v[50:51], v[50:51], v[0:1] op_sel_hi:[1,0]
	v_pk_mul_f32 v[48:49], v[48:49], v[0:1] op_sel_hi:[1,0]
	v_pk_mul_f32 v[46:47], v[46:47], v[0:1] op_sel_hi:[1,0]
	v_pk_mul_f32 v[44:45], v[44:45], v[0:1] op_sel_hi:[1,0]
	v_pk_mul_f32 v[42:43], v[42:43], v[0:1] op_sel_hi:[1,0]
	v_pk_mul_f32 v[40:41], v[40:41], v[0:1] op_sel_hi:[1,0]
	s_branch .LBB0_1221
